# GU phases (s=0,10) replaced by hand-written 256x256-tile 8-phase GEMM K-loop (2-buffer LDS-DMA ring, staggered wave halves, cross-tile streaming)
# speedup vs baseline: 1.7836x; 1.7836x over previous
; DI void gemm_gu(const Params& p, size_t woff, int bid, int nb, char* smem, const int tid) {
;     const bf16_t* A = (const bf16_t*)(p.ws + B_XN);
;     const bf16_t* Bt = (const bf16_t*)(p.ws + woff);
;     bf16_t* ACT = (bf16_t*)(p.ws + B_ACT);
;     const int ntn = 44, ntiles = 130 * ntn;
;     const int lane = tid & 63, wave = __builtin_amdgcn_readfirstlane(tid >> 6), wm = wave >> 1, wn = wave & 1, r = lane & 15, q = lane >> 4;
;     TileIter ti; ti.init(65, ntn, bid, nb);
;     int tm, tn, tm2 = 0, tn2 = 0;
;     bool have = ti.next(tm, tn);
;     Ring rg; rg.st = 0; rg.primed = 0;
; DI void run_phase(const Params& pk, int ph, int bid_, int nb, char* smem) {
;     ...
;     const int l = (ph - 1) / 15, s = (ph - 1) % 15;
;     switch (s) {
;     case 0: gemm_gu(p, W_GU1, bid, nb, smem, tid); break;
;     case 1: gemm_y(p, (const bf16_t*)(p.ws + B_ACT), DFF, W_DN1, DFF, 4, bid, nb, smem, tid); break;
;     case 2: rowpass(p, false, 0.5f, p.in[12] + l * DM, p.in[15] + l * DM, 11, bid, nb, tid); break;
;     case 3: gemm_in(p, l, bid, nb, smem, tid); break;
;     case 4: post_phase(p, l, bid, nb, tid); break;
;     case 5: gemm_uqkv(p, bid, nb, smem, tid); break;
;     case 6: attn_phase(p, bid, nb, smem, tid); break;
;     case 7: onorm_pass(p, p.in[23] + l * DM, bid, nb, tid); break;
;     case 8: gemm_y(p, (const bf16_t*)(p.ws + B_XN), DM, W_OUT, DM, 2, bid, nb, smem, tid); break;
;     case 9: rowpass(p, false, 1.0f, p.in[16] + l * DM, p.in[25] + l * DM, 8, bid, nb, tid); break;
;     case 10: gemm_gu(p, W_GU2, bid, nb, smem, tid); break;
.LBB0_195:
	s_andn2_b64 vcc, exec, s[0:1]
	s_cbranch_vccnz .LBB0_276
	v_readlane_b32 s0, v231, 5
	s_cmp_lt_i32 s0, 9
	s_mov_b64 s[0:1], -1
	s_cbranch_scc1 .LBB0_237
	v_readlane_b32 s0, v231, 5
	s_cmp_gt_i32 s0, 9
	s_mov_b64 s[0:1], -1
	s_cbranch_scc0 .LBB0_226
	s_mov_b32 s61, 0x1720000
	s_branch .Lgu_entry

; #define BAR() { __builtin_amdgcn_sched_barrier(0); __builtin_amdgcn_s_barrier(); asm volatile("" ::: "memory"); __builtin_amdgcn_sched_barrier(0); }
; DI void gemm_stream2(const bf16_t* __restrict__ A, int lda, const bf16_t* __restrict__ Bt, int ldb, int K, int m0, int n0, ...
;     ...
;     int st = rg.st;
;     if (!rg.primed) {
;         const int s1p = st == 2 ? 0 : st + 1;
;         BAR();
;         STAGE(st, 0);
;         STAGE(s1p, 1);
;         asm volatile("s_waitcnt vmcnt(6)" ::: "memory");
;         BAR();
;     }
;     if (grp == 1) BAR();
;     DI void init(int ntm_, int ntn_, int bid, int nb) {
;         ntm = ntm_; ntn = ntn_;
;         const int nt = ntm * ntn;
;         if ((nb & 7) == 0) { const int x = bid & 7, per = (nt + 7) >> 3; L = x * per + (bid >> 3); end = min((x + 1) * per, nt); step = nb >> 3; }
;         else { L = bid; end = nt; step = nb; }
;     }
;     DI bool next(int& tm, int& tn) {
;         if (L >= end) return false;
;         const int gsz = 8 * ntn, grp = L / gsz, rem = L - grp * gsz, rows = min(8, ntm - grp * 8);
;         tn = rem / rows; tm = grp * 8 + (rem - tn * rows);
;         L += step; return true;
;     }
; DI void zero_acc(f32x4 (&acc)[4][4]) {
; #pragma unroll
;     for (int i = 0; i < 4; ++i)
; #pragma unroll
;         for (int j = 0; j < 4; ++j) acc[i][j] = (f32x4){0.f, 0.f, 0.f, 0.f};
; }
; DI void gemm_gu(const Params& p, size_t woff, int bid, int nb, char* smem, const int tid) {
;     const bf16_t* A = (const bf16_t*)(p.ws + B_XN);
;     const bf16_t* Bt = (const bf16_t*)(p.ws + woff);
;     bf16_t* ACT = (bf16_t*)(p.ws + B_ACT);
;     const int ntn = 44, ntiles = 130 * ntn;
;     const int lane = tid & 63, wave = __builtin_amdgcn_readfirstlane(tid >> 6), wm = wave >> 1, wn = wave & 1, r = lane & 15, q = lane >> 4;
;     TileIter ti; ti.init(65, ntn, bid, nb);
;     int tm, tn, tm2 = 0, tn2 = 0;
;     bool have = ti.next(tm, tn);
;     Ring rg; rg.st = 0; rg.primed = 0;
;     for (; have; tm = tm2, tn = tn2) {
;         have = ti.next(tm2, tn2);
;         const int m0 = tm * 256, n0 = tn * 128;
;         f32x4 acc[4][4]; zero_acc(acc);
;         gemm_stream(A, 1024, Bt, 1024, 1024, m0, n0, have, tm2 * 256, tn2 * 128, smem, acc, tid, rg);
.LBB0_749:
	s_andn2_b64 vcc, exec, s[0:1]
	s_cbranch_vccnz .LBB0_779
	v_readlane_b32 s0, v231, 5
	s_cmp_lg_u32 s0, 0
	s_cbranch_scc1 .LBB0_779
	s_mov_b32 s61, 0
.Lgu_entry:
	v_readlane_b32 s51, v240, 0
	v_readlane_b32 s53, v238, 54
	v_readfirstlane_b32 s10, v193
	s_nop 3
	s_lshr_b32 s10, s10, 6
	s_lshr_b32 s33, s10, 2
	s_and_b32 s36, s10, 3
	s_lshl_b32 s39, s10, 11
	s_add_i32 s39, s39, 16
	s_and_b32 s1, s53, 7
	s_cmp_eq_u32 s1, 0
	s_cbranch_scc0 .Lgu_simple
	s_and_b32 s1, s51, 7
	s_lshr_b32 s2, s51, 3
	s_mul_i32 s3, s1, 0xb3
	s_add_i32 s51, s3, s2
	s_add_i32 s52, s3, 0xb3
	s_min_u32 s52, s52, 0x596
	s_lshr_b32 s53, s53, 3
	s_branch .Lgu_ranged
.Lgu_simple:
	s_movk_i32 s52, 0x596
.Lgu_ranged:
	s_cmp_ge_u32 s51, s52
	s_cbranch_scc1 .LBB0_860
	v_and_b32_e32 v190, 63, v193
	v_and_b32_e32 v191, 15, v190
	v_lshrrev_b32_e32 v17, 4, v190
	v_lshrrev_b32_e32 v18, 3, v190
	v_and_b32_e32 v19, 7, v190
	v_xor_b32_e32 v195, v19, v17
	v_lshlrev_b32_e32 v195, 4, v195
	v_lshl_add_u32 v184, v18, 11, v195
	v_or_b32_e32 v195, 4, v17
	v_xor_b32_e32 v195, v19, v195
	v_lshlrev_b32_e32 v195, 4, v195
	v_add_u32_e32 v227, 8, v18
	v_lshl_add_u32 v185, v227, 11, v195
	v_lshrrev_b32_e32 v195, 1, v191
	v_xor_b32_e32 v195, v17, v195
	v_lshlrev_b32_e32 v195, 4, v195
	s_lshl_b32 s1, s33, 6
	v_add_u32_e32 v227, s1, v191
	v_lshl_add_u32 v186, v227, 7, v195
	v_xor_b32_e32 v187, 64, v186
	v_mul_u32_u24_e32 v228, 0x1600, v227
	s_lshl_b32 s1, s36, 5
	v_add_u32_e32 v227, s1, v191
	v_lshl_add_u32 v188, v227, 7, v195
	v_add_u32_e32 v188, 0x10000, v188
	v_xor_b32_e32 v189, 64, v188
	v_lshl_add_u32 v229, v17, 3, s1
	v_add_u32_e32 v237, v228, v229
	s_mul_i32 s1, s51, 0x1745e
	s_lshr_b32 s2, s1, 24
	s_mul_i32 s1, s2, 0xb0
	s_sub_u32 s1, s51, s1
	s_lshr_b32 s3, s1, 3
	s_and_b32 s37, s1, 7
	s_cmp_lt_u32 s2, 8
	s_cselect_b32 s58, s3, s1
	s_cselect_b32 s37, s37, 0
	s_lshl_b32 s2, s2, 3
	s_add_i32 s57, s2, s37
	s_lshl_b32 s1, s57, 19
	s_lshl_b32 s2, s10, 15
	s_add_u32 s1, s1, s2
	s_add_u32 s1, s1, 0x3240000
	s_add_u32 s66, s88, s1
	s_addc_u32 s67, s89, 0
	s_add_u32 s68, s66, 0x40000
	s_addc_u32 s69, s67, 0
	s_lshl_b32 s1, s58, 19
	s_add_u32 s1, s1, s2
	s_add_u32 s1, s1, s61
	s_add_u32 s70, s88, s1
	s_addc_u32 s71, s89, 0
	s_add_u32 s72, s70, 0x40000
	s_addc_u32 s73, s71, 0
	s_add_i32 m0, s39, 0x10000
	s_nop 0
	global_load_lds_dwordx4 v184, s[70:71]
	s_add_i32 m0, s39, 0x10400
	s_nop 0
	global_load_lds_dwordx4 v185, s[70:71]
	s_add_u32 s70, s70, 0x80
	s_addc_u32 s71, s71, 0
	s_add_i32 m0, s39, 0x0
	s_nop 0
	global_load_lds_dwordx4 v184, s[66:67]
	s_add_i32 m0, s39, 0x400
	s_nop 0
	global_load_lds_dwordx4 v185, s[66:67]
	s_add_u32 s66, s66, 0x80
	s_addc_u32 s67, s67, 0
	s_add_i32 m0, s39, 0x14000
	s_nop 0
	global_load_lds_dwordx4 v184, s[72:73]
	s_add_i32 m0, s39, 0x14400
	s_nop 0
	global_load_lds_dwordx4 v185, s[72:73]
	s_add_u32 s72, s72, 0x80
	s_addc_u32 s73, s73, 0
	s_add_i32 m0, s39, 0x4000
	s_nop 0
	global_load_lds_dwordx4 v184, s[68:69]
	s_add_i32 m0, s39, 0x4400
	s_nop 0
	global_load_lds_dwordx4 v185, s[68:69]
	s_add_u32 s68, s68, 0x80
	s_addc_u32 s69, s69, 0
	s_cmp_eq_u32 s33, 0
	s_cbranch_scc1 .Lgu_lead
	s_barrier
.Lgu_lead:
	s_waitcnt vmcnt(4)
	s_barrier
	s_add_i32 m0, s39, 0x18000
	s_nop 0
	global_load_lds_dwordx4 v184, s[70:71]
	s_add_i32 m0, s39, 0x18400
	s_nop 0
	global_load_lds_dwordx4 v185, s[70:71]
	s_add_u32 s70, s70, 0x80
	s_addc_u32 s71, s71, 0
	s_add_i32 m0, s39, 0x8000
	s_nop 0
	global_load_lds_dwordx4 v184, s[66:67]
	s_add_i32 m0, s39, 0x8400
	s_nop 0
	global_load_lds_dwordx4 v185, s[66:67]
	s_add_u32 s66, s66, 0x80
	s_addc_u32 s67, s67, 0
	s_add_i32 m0, s39, 0x1c000
	s_nop 0
	global_load_lds_dwordx4 v184, s[72:73]
	s_add_i32 m0, s39, 0x1c400
	s_nop 0
	global_load_lds_dwordx4 v185, s[72:73]
	s_add_u32 s72, s72, 0x80
	s_addc_u32 s73, s73, 0
	s_waitcnt vmcnt(6)
	s_barrier
.Lgu_tile:
	s_add_u32 s76, s51, s53
	s_cmp_lt_u32 s76, s52
	s_cselect_b32 s54, 1, 0
	s_cbranch_scc0 .Lgu_nonext
	s_mul_i32 s1, s76, 0x1745e
	s_lshr_b32 s2, s1, 24
	s_mul_i32 s1, s2, 0xb0
	s_sub_u32 s1, s76, s1
	s_lshr_b32 s3, s1, 3
	s_and_b32 s37, s1, 7
	s_cmp_lt_u32 s2, 8
	s_cselect_b32 s60, s3, s1
	s_cselect_b32 s37, s37, 0
	s_lshl_b32 s2, s2, 3
	s_add_i32 s59, s2, s37
	s_lshl_b32 s1, s59, 19
	s_lshl_b32 s2, s10, 15
	s_add_u32 s1, s1, s2
	s_add_u32 s1, s1, 0x3240000
	s_add_u32 s74, s88, s1
	s_addc_u32 s75, s89, 0
	s_add_u32 s78, s74, 0x40000
	s_addc_u32 s79, s75, 0
	s_lshl_b32 s1, s60, 19
	s_add_u32 s1, s1, s2
	s_add_u32 s1, s1, s61
	s_add_u32 s80, s88, s1
	s_addc_u32 s81, s89, 0
	s_add_u32 s82, s80, 0x40000
	s_addc_u32 s83, s81, 0
.Lgu_nonext:
	v_mov_b64_e32 v[24:25], 0
	v_mov_b64_e32 v[26:27], 0
	v_mov_b64_e32 v[28:29], 0
	v_mov_b64_e32 v[30:31], 0
	v_mov_b64_e32 v[32:33], 0
	v_mov_b64_e32 v[34:35], 0
	v_mov_b64_e32 v[36:37], 0
	v_mov_b64_e32 v[38:39], 0
	v_mov_b64_e32 v[40:41], 0
	v_mov_b64_e32 v[42:43], 0
	v_mov_b64_e32 v[44:45], 0
	v_mov_b64_e32 v[46:47], 0
	v_mov_b64_e32 v[48:49], 0
	v_mov_b64_e32 v[50:51], 0
	v_mov_b64_e32 v[52:53], 0
	v_mov_b64_e32 v[54:55], 0
	v_mov_b64_e32 v[56:57], 0
	v_mov_b64_e32 v[58:59], 0
	v_mov_b64_e32 v[60:61], 0
	v_mov_b64_e32 v[62:63], 0
	v_mov_b64_e32 v[64:65], 0
	v_mov_b64_e32 v[66:67], 0
	v_mov_b64_e32 v[68:69], 0
	v_mov_b64_e32 v[70:71], 0
	v_mov_b64_e32 v[72:73], 0
	v_mov_b64_e32 v[74:75], 0
	v_mov_b64_e32 v[76:77], 0
	v_mov_b64_e32 v[78:79], 0
	v_mov_b64_e32 v[80:81], 0
	v_mov_b64_e32 v[82:83], 0
	v_mov_b64_e32 v[84:85], 0
	v_mov_b64_e32 v[86:87], 0
	v_mov_b64_e32 v[88:89], 0
	v_mov_b64_e32 v[90:91], 0
	v_mov_b64_e32 v[92:93], 0
	v_mov_b64_e32 v[94:95], 0
	v_mov_b64_e32 v[96:97], 0
	v_mov_b64_e32 v[98:99], 0
	v_mov_b64_e32 v[100:101], 0
	v_mov_b64_e32 v[102:103], 0
	v_mov_b64_e32 v[104:105], 0
	v_mov_b64_e32 v[106:107], 0
	v_mov_b64_e32 v[108:109], 0
	v_mov_b64_e32 v[110:111], 0
	v_mov_b64_e32 v[112:113], 0
	v_mov_b64_e32 v[114:115], 0
	v_mov_b64_e32 v[116:117], 0
	v_mov_b64_e32 v[118:119], 0
	v_mov_b64_e32 v[120:121], 0
	v_mov_b64_e32 v[122:123], 0
	v_mov_b64_e32 v[124:125], 0
	v_mov_b64_e32 v[126:127], 0
	v_mov_b64_e32 v[128:129], 0
	v_mov_b64_e32 v[130:131], 0
	v_mov_b64_e32 v[132:133], 0
	v_mov_b64_e32 v[134:135], 0
	v_mov_b64_e32 v[136:137], 0
	v_mov_b64_e32 v[138:139], 0
	v_mov_b64_e32 v[140:141], 0
	v_mov_b64_e32 v[142:143], 0
	v_mov_b64_e32 v[144:145], 0
	v_mov_b64_e32 v[146:147], 0
	v_mov_b64_e32 v[148:149], 0
	v_mov_b64_e32 v[150:151], 0
	s_add_u32 s0, s54, 7
; #define LAS __attribute__((address_space(3)))
; #define BAR() { __builtin_amdgcn_sched_barrier(0); __builtin_amdgcn_s_barrier(); asm volatile("" ::: "memory"); __builtin_amdgcn_sched_barrier(0); }
; DI void gemm_stream2(const bf16_t* __restrict__ A, int lda, const bf16_t* __restrict__ Bt, int ldb, int K, int m0, int n0, ...
;     ...
;     for (int kt = 0; kt < nk; ++kt) {
;         const bool pf = (kt + 2 < nk) || has_next, more = (kt + 1 < nk) || has_next;
;         const bf16_t* pa = (kt + 2 < nk) ? ga + (kt + 2) * 64 : gan + (kt + 2 - nk) * 64;
;         const bf16_t* pb = (kt + 2 < nk) ? gb + (kt + 2) * 64 : gbn + (kt + 2 - nk) * 64;
;         const int plda = (kt + 2 < nk) ? lda : ldan, pldb = (kt + 2 < nk) ? ldb : ldbn;
;         const int s2 = st >= 1 ? st - 1 : 2;
;         const LAS char* base = lds + st * 49152;
; #pragma unroll
;         for (int ks = 0; ks < 2; ++ks) {
;             const unsigned fo = ks ? fo1 : fo0;
;             bf16x8 af[4], bfr[4];
; #pragma unroll
;             for (int i = 0; i < 4; ++i) { af[i] = *(const LAS bf16x8*)(base + aoff + i * 2048 + fo); bfr[i] = *(const LAS bf16x8*)(base + boff + i * 2048 + fo); }
;             if (ks == 1 && more) { if (pf) asm volatile("s_waitcnt vmcnt(3)" ::: "memory"); else asm volatile("s_waitcnt vmcnt(0)" ::: "memory"); }
;             if (pf) { PIECE(s2, ks * 3 + 0); PIECE(s2, ks * 3 + 1); PIECE(s2, ks * 3 + 2); }
;             asm volatile("s_waitcnt lgkmcnt(0)" ::: "memory");
;             BAR();
;             __builtin_amdgcn_s_setprio(1);
; #pragma unroll
;             for (int mi = 0; mi < 4; ++mi)
; #pragma unroll
;                 for (int ni = 0; ni < 4; ++ni) acc[mi][ni] = __builtin_amdgcn_mfma_f32_16x16x32_bf16(bfr[ni], af[mi], acc[mi][ni], 0, 0, 0);
;             __builtin_amdgcn_s_setprio(0);
;             BAR();
;         }
.Lgu_kloop:
	ds_read_b128 v[0:3], v188 offset:16
	ds_read_b128 v[4:7], v189 offset:16
	ds_read_b128 v[8:11], v188 offset:2064
	ds_read_b128 v[12:15], v189 offset:2064
	ds_read_b128 v[152:155], v186 offset:16
	ds_read_b128 v[156:159], v187 offset:16
	ds_read_b128 v[160:163], v186 offset:2064
	ds_read_b128 v[164:167], v187 offset:2064
	ds_read_b128 v[168:171], v186 offset:4112
	ds_read_b128 v[172:175], v187 offset:4112
	ds_read_b128 v[176:179], v186 offset:6160
	ds_read_b128 v[180:183], v187 offset:6160
	s_add_i32 m0, s39, 0xc000
	s_nop 0
	global_load_lds_dwordx4 v184, s[68:69]
	s_add_i32 m0, s39, 0xc400
	s_nop 0
	global_load_lds_dwordx4 v185, s[68:69]
	s_add_u32 s68, s68, 0x80
	s_addc_u32 s69, s69, 0
	s_cmp_lg_u32 s0, s54
	s_cbranch_scc1 .Lgu_nosw1
	s_mov_b64 s[66:67], s[74:75]
	s_mov_b64 s[68:69], s[78:79]
	s_mov_b64 s[70:71], s[80:81]
	s_mov_b64 s[72:73], s[82:83]
.Lgu_nosw1:
	s_waitcnt lgkmcnt(8)
	s_barrier
	s_waitcnt lgkmcnt(0)
	s_setprio 1
	v_mfma_f32_16x16x32_bf16 v[24:27], v[0:3], v[152:155], v[24:27]
	v_mfma_f32_16x16x32_bf16 v[28:31], v[8:11], v[152:155], v[28:31]
	v_mfma_f32_16x16x32_bf16 v[32:35], v[0:3], v[160:163], v[32:35]
	v_mfma_f32_16x16x32_bf16 v[36:39], v[8:11], v[160:163], v[36:39]
	v_mfma_f32_16x16x32_bf16 v[40:43], v[0:3], v[168:171], v[40:43]
	v_mfma_f32_16x16x32_bf16 v[44:47], v[8:11], v[168:171], v[44:47]
	v_mfma_f32_16x16x32_bf16 v[48:51], v[0:3], v[176:179], v[48:51]
	v_mfma_f32_16x16x32_bf16 v[52:55], v[8:11], v[176:179], v[52:55]
	v_mfma_f32_16x16x32_bf16 v[24:27], v[4:7], v[156:159], v[24:27]
	v_mfma_f32_16x16x32_bf16 v[28:31], v[12:15], v[156:159], v[28:31]
	v_mfma_f32_16x16x32_bf16 v[32:35], v[4:7], v[164:167], v[32:35]
	v_mfma_f32_16x16x32_bf16 v[36:39], v[12:15], v[164:167], v[36:39]
	v_mfma_f32_16x16x32_bf16 v[40:43], v[4:7], v[172:175], v[40:43]
	v_mfma_f32_16x16x32_bf16 v[44:47], v[12:15], v[172:175], v[44:47]
	v_mfma_f32_16x16x32_bf16 v[48:51], v[4:7], v[180:183], v[48:51]
	v_mfma_f32_16x16x32_bf16 v[52:55], v[12:15], v[180:183], v[52:55]
	s_setprio 0
	s_barrier
	ds_read_b128 v[196:199], v188 offset:16400
	ds_read_b128 v[200:203], v189 offset:16400
	ds_read_b128 v[204:207], v188 offset:18448
	ds_read_b128 v[208:211], v189 offset:18448
	s_add_i32 m0, s39, 0x10000
	s_nop 0
	global_load_lds_dwordx4 v184, s[70:71]
	s_add_i32 m0, s39, 0x10400
	s_nop 0
	global_load_lds_dwordx4 v185, s[70:71]
	s_add_u32 s70, s70, 0x80
	s_addc_u32 s71, s71, 0
	s_barrier
	s_waitcnt lgkmcnt(0)
	s_setprio 1
	v_mfma_f32_16x16x32_bf16 v[56:59], v[196:199], v[152:155], v[56:59]
	v_mfma_f32_16x16x32_bf16 v[60:63], v[204:207], v[152:155], v[60:63]
	v_mfma_f32_16x16x32_bf16 v[64:67], v[196:199], v[160:163], v[64:67]
	v_mfma_f32_16x16x32_bf16 v[68:71], v[204:207], v[160:163], v[68:71]
	v_mfma_f32_16x16x32_bf16 v[72:75], v[196:199], v[168:171], v[72:75]
	v_mfma_f32_16x16x32_bf16 v[76:79], v[204:207], v[168:171], v[76:79]
	v_mfma_f32_16x16x32_bf16 v[80:83], v[196:199], v[176:179], v[80:83]
	v_mfma_f32_16x16x32_bf16 v[84:87], v[204:207], v[176:179], v[84:87]
	v_mfma_f32_16x16x32_bf16 v[56:59], v[200:203], v[156:159], v[56:59]
	v_mfma_f32_16x16x32_bf16 v[60:63], v[208:211], v[156:159], v[60:63]
	v_mfma_f32_16x16x32_bf16 v[64:67], v[200:203], v[164:167], v[64:67]
	v_mfma_f32_16x16x32_bf16 v[68:71], v[208:211], v[164:167], v[68:71]
	v_mfma_f32_16x16x32_bf16 v[72:75], v[200:203], v[172:175], v[72:75]
	v_mfma_f32_16x16x32_bf16 v[76:79], v[208:211], v[172:175], v[76:79]
	v_mfma_f32_16x16x32_bf16 v[80:83], v[200:203], v[180:183], v[80:83]
	v_mfma_f32_16x16x32_bf16 v[84:87], v[208:211], v[180:183], v[84:87]
	s_setprio 0
	s_barrier
	ds_read_b128 v[152:155], v186 offset:16400
	ds_read_b128 v[156:159], v187 offset:16400
	ds_read_b128 v[160:163], v186 offset:18448
	ds_read_b128 v[164:167], v187 offset:18448
	ds_read_b128 v[168:171], v186 offset:20496
	ds_read_b128 v[172:175], v187 offset:20496
	ds_read_b128 v[176:179], v186 offset:22544
	ds_read_b128 v[180:183], v187 offset:22544
	s_add_i32 m0, s39, 0x0
	s_nop 0
	global_load_lds_dwordx4 v184, s[66:67]
	s_add_i32 m0, s39, 0x400
	s_nop 0
	global_load_lds_dwordx4 v185, s[66:67]
	s_add_u32 s66, s66, 0x80
	s_addc_u32 s67, s67, 0
	s_barrier
	s_waitcnt lgkmcnt(0)
	s_setprio 1
	v_mfma_f32_16x16x32_bf16 v[88:91], v[0:3], v[152:155], v[88:91]
	v_mfma_f32_16x16x32_bf16 v[92:95], v[8:11], v[152:155], v[92:95]
	v_mfma_f32_16x16x32_bf16 v[96:99], v[0:3], v[160:163], v[96:99]
	v_mfma_f32_16x16x32_bf16 v[100:103], v[8:11], v[160:163], v[100:103]
	v_mfma_f32_16x16x32_bf16 v[104:107], v[0:3], v[168:171], v[104:107]
	v_mfma_f32_16x16x32_bf16 v[108:111], v[8:11], v[168:171], v[108:111]
	v_mfma_f32_16x16x32_bf16 v[112:115], v[0:3], v[176:179], v[112:115]
	v_mfma_f32_16x16x32_bf16 v[116:119], v[8:11], v[176:179], v[116:119]
	v_mfma_f32_16x16x32_bf16 v[88:91], v[4:7], v[156:159], v[88:91]
	v_mfma_f32_16x16x32_bf16 v[92:95], v[12:15], v[156:159], v[92:95]
	v_mfma_f32_16x16x32_bf16 v[96:99], v[4:7], v[164:167], v[96:99]
	v_mfma_f32_16x16x32_bf16 v[100:103], v[12:15], v[164:167], v[100:103]
	v_mfma_f32_16x16x32_bf16 v[104:107], v[4:7], v[172:175], v[104:107]
	v_mfma_f32_16x16x32_bf16 v[108:111], v[12:15], v[172:175], v[108:111]
	v_mfma_f32_16x16x32_bf16 v[112:115], v[4:7], v[180:183], v[112:115]
	v_mfma_f32_16x16x32_bf16 v[116:119], v[12:15], v[180:183], v[116:119]
	s_setprio 0
	s_barrier
	s_add_i32 m0, s39, 0x14000
	s_nop 0
	global_load_lds_dwordx4 v184, s[72:73]
	s_add_i32 m0, s39, 0x14400
	s_nop 0
	global_load_lds_dwordx4 v185, s[72:73]
	s_add_u32 s72, s72, 0x80
	s_addc_u32 s73, s73, 0
	s_waitcnt vmcnt(6)
	s_barrier
; #define LAS __attribute__((address_space(3)))
; #define BAR() { __builtin_amdgcn_sched_barrier(0); __builtin_amdgcn_s_barrier(); asm volatile("" ::: "memory"); __builtin_amdgcn_sched_barrier(0); }
; DI void gemm_stream2(const bf16_t* __restrict__ A, int lda, const bf16_t* __restrict__ Bt, int ldb, int K, int m0, int n0, ...
;     ...
;     for (int kt = 0; kt < nk; ++kt) {
;         const bool pf = (kt + 2 < nk) || has_next, more = (kt + 1 < nk) || has_next;
;         const bf16_t* pa = (kt + 2 < nk) ? ga + (kt + 2) * 64 : gan + (kt + 2 - nk) * 64;
;         const bf16_t* pb = (kt + 2 < nk) ? gb + (kt + 2) * 64 : gbn + (kt + 2 - nk) * 64;
;         const int plda = (kt + 2 < nk) ? lda : ldan, pldb = (kt + 2 < nk) ? ldb : ldbn;
;         const int s2 = st >= 1 ? st - 1 : 2;
;         const LAS char* base = lds + st * 49152;
; #pragma unroll
;         for (int ks = 0; ks < 2; ++ks) {
;             const unsigned fo = ks ? fo1 : fo0;
;             bf16x8 af[4], bfr[4];
; #pragma unroll
;             for (int i = 0; i < 4; ++i) { af[i] = *(const LAS bf16x8*)(base + aoff + i * 2048 + fo); bfr[i] = *(const LAS bf16x8*)(base + boff + i * 2048 + fo); }
;             if (ks == 1 && more) { if (pf) asm volatile("s_waitcnt vmcnt(3)" ::: "memory"); else asm volatile("s_waitcnt vmcnt(0)" ::: "memory"); }
;             if (pf) { PIECE(s2, ks * 3 + 0); PIECE(s2, ks * 3 + 1); PIECE(s2, ks * 3 + 2); }
;             asm volatile("s_waitcnt lgkmcnt(0)" ::: "memory");
;             BAR();
;             __builtin_amdgcn_s_setprio(1);
; #pragma unroll
;             for (int mi = 0; mi < 4; ++mi)
; #pragma unroll
;                 for (int ni = 0; ni < 4; ++ni) acc[mi][ni] = __builtin_amdgcn_mfma_f32_16x16x32_bf16(bfr[ni], af[mi], acc[mi][ni], 0, 0, 0);
;             __builtin_amdgcn_s_setprio(0);
;             BAR();
;         }
	s_setprio 1
	v_mfma_f32_16x16x32_bf16 v[120:123], v[196:199], v[152:155], v[120:123]
	v_mfma_f32_16x16x32_bf16 v[124:127], v[204:207], v[152:155], v[124:127]
	v_mfma_f32_16x16x32_bf16 v[128:131], v[196:199], v[160:163], v[128:131]
	v_mfma_f32_16x16x32_bf16 v[132:135], v[204:207], v[160:163], v[132:135]
	v_mfma_f32_16x16x32_bf16 v[136:139], v[196:199], v[168:171], v[136:139]
	v_mfma_f32_16x16x32_bf16 v[140:143], v[204:207], v[168:171], v[140:143]
	v_mfma_f32_16x16x32_bf16 v[144:147], v[196:199], v[176:179], v[144:147]
	v_mfma_f32_16x16x32_bf16 v[148:151], v[204:207], v[176:179], v[148:151]
	v_mfma_f32_16x16x32_bf16 v[120:123], v[200:203], v[156:159], v[120:123]
	v_mfma_f32_16x16x32_bf16 v[124:127], v[208:211], v[156:159], v[124:127]
	v_mfma_f32_16x16x32_bf16 v[128:131], v[200:203], v[164:167], v[128:131]
	v_mfma_f32_16x16x32_bf16 v[132:135], v[208:211], v[164:167], v[132:135]
	v_mfma_f32_16x16x32_bf16 v[136:139], v[200:203], v[172:175], v[136:139]
	v_mfma_f32_16x16x32_bf16 v[140:143], v[208:211], v[172:175], v[140:143]
	v_mfma_f32_16x16x32_bf16 v[144:147], v[200:203], v[180:183], v[144:147]
	v_mfma_f32_16x16x32_bf16 v[148:151], v[208:211], v[180:183], v[148:151]
	s_setprio 0
	s_barrier
	ds_read_b128 v[0:3], v188 offset:32784
	ds_read_b128 v[4:7], v189 offset:32784
	ds_read_b128 v[8:11], v188 offset:34832
	ds_read_b128 v[12:15], v189 offset:34832
	ds_read_b128 v[152:155], v186 offset:32784
	ds_read_b128 v[156:159], v187 offset:32784
	ds_read_b128 v[160:163], v186 offset:34832
	ds_read_b128 v[164:167], v187 offset:34832
	ds_read_b128 v[168:171], v186 offset:36880
	ds_read_b128 v[172:175], v187 offset:36880
	ds_read_b128 v[176:179], v186 offset:38928
	ds_read_b128 v[180:183], v187 offset:38928
	s_add_i32 m0, s39, 0x4000
	s_nop 0
	global_load_lds_dwordx4 v184, s[68:69]
	s_add_i32 m0, s39, 0x4400
	s_nop 0
	global_load_lds_dwordx4 v185, s[68:69]
	s_add_u32 s68, s68, 0x80
	s_addc_u32 s69, s69, 0
	s_waitcnt lgkmcnt(8)
	s_barrier
	s_waitcnt lgkmcnt(0)
	s_setprio 1
	v_mfma_f32_16x16x32_bf16 v[24:27], v[0:3], v[152:155], v[24:27]
	v_mfma_f32_16x16x32_bf16 v[28:31], v[8:11], v[152:155], v[28:31]
	v_mfma_f32_16x16x32_bf16 v[32:35], v[0:3], v[160:163], v[32:35]
	v_mfma_f32_16x16x32_bf16 v[36:39], v[8:11], v[160:163], v[36:39]
	v_mfma_f32_16x16x32_bf16 v[40:43], v[0:3], v[168:171], v[40:43]
	v_mfma_f32_16x16x32_bf16 v[44:47], v[8:11], v[168:171], v[44:47]
	v_mfma_f32_16x16x32_bf16 v[48:51], v[0:3], v[176:179], v[48:51]
	v_mfma_f32_16x16x32_bf16 v[52:55], v[8:11], v[176:179], v[52:55]
	v_mfma_f32_16x16x32_bf16 v[24:27], v[4:7], v[156:159], v[24:27]
	v_mfma_f32_16x16x32_bf16 v[28:31], v[12:15], v[156:159], v[28:31]
	v_mfma_f32_16x16x32_bf16 v[32:35], v[4:7], v[164:167], v[32:35]
	v_mfma_f32_16x16x32_bf16 v[36:39], v[12:15], v[164:167], v[36:39]
	v_mfma_f32_16x16x32_bf16 v[40:43], v[4:7], v[172:175], v[40:43]
	v_mfma_f32_16x16x32_bf16 v[44:47], v[12:15], v[172:175], v[44:47]
	v_mfma_f32_16x16x32_bf16 v[48:51], v[4:7], v[180:183], v[48:51]
	v_mfma_f32_16x16x32_bf16 v[52:55], v[12:15], v[180:183], v[52:55]
	s_setprio 0
	s_barrier
	ds_read_b128 v[196:199], v188 offset:49168
	ds_read_b128 v[200:203], v189 offset:49168
	ds_read_b128 v[204:207], v188 offset:51216
	ds_read_b128 v[208:211], v189 offset:51216
	s_add_i32 m0, s39, 0x18000
	s_nop 0
	global_load_lds_dwordx4 v184, s[70:71]
	s_add_i32 m0, s39, 0x18400
	s_nop 0
	global_load_lds_dwordx4 v185, s[70:71]
	s_add_u32 s70, s70, 0x80
	s_addc_u32 s71, s71, 0
	s_barrier
	s_waitcnt lgkmcnt(0)
	s_setprio 1
	v_mfma_f32_16x16x32_bf16 v[56:59], v[196:199], v[152:155], v[56:59]
	v_mfma_f32_16x16x32_bf16 v[60:63], v[204:207], v[152:155], v[60:63]
	v_mfma_f32_16x16x32_bf16 v[64:67], v[196:199], v[160:163], v[64:67]
	v_mfma_f32_16x16x32_bf16 v[68:71], v[204:207], v[160:163], v[68:71]
	v_mfma_f32_16x16x32_bf16 v[72:75], v[196:199], v[168:171], v[72:75]
	v_mfma_f32_16x16x32_bf16 v[76:79], v[204:207], v[168:171], v[76:79]
	v_mfma_f32_16x16x32_bf16 v[80:83], v[196:199], v[176:179], v[80:83]
	v_mfma_f32_16x16x32_bf16 v[84:87], v[204:207], v[176:179], v[84:87]
	v_mfma_f32_16x16x32_bf16 v[56:59], v[200:203], v[156:159], v[56:59]
	v_mfma_f32_16x16x32_bf16 v[60:63], v[208:211], v[156:159], v[60:63]
	v_mfma_f32_16x16x32_bf16 v[64:67], v[200:203], v[164:167], v[64:67]
	v_mfma_f32_16x16x32_bf16 v[68:71], v[208:211], v[164:167], v[68:71]
	v_mfma_f32_16x16x32_bf16 v[72:75], v[200:203], v[172:175], v[72:75]
	v_mfma_f32_16x16x32_bf16 v[76:79], v[208:211], v[172:175], v[76:79]
	v_mfma_f32_16x16x32_bf16 v[80:83], v[200:203], v[180:183], v[80:83]
	v_mfma_f32_16x16x32_bf16 v[84:87], v[208:211], v[180:183], v[84:87]
	s_setprio 0
	s_barrier
	ds_read_b128 v[152:155], v186 offset:49168
	ds_read_b128 v[156:159], v187 offset:49168
	ds_read_b128 v[160:163], v186 offset:51216
	ds_read_b128 v[164:167], v187 offset:51216
	ds_read_b128 v[168:171], v186 offset:53264
	ds_read_b128 v[172:175], v187 offset:53264
	ds_read_b128 v[176:179], v186 offset:55312
	ds_read_b128 v[180:183], v187 offset:55312
	s_add_i32 m0, s39, 0x8000
	s_nop 0
	global_load_lds_dwordx4 v184, s[66:67]
	s_add_i32 m0, s39, 0x8400
	s_nop 0
	global_load_lds_dwordx4 v185, s[66:67]
	s_add_u32 s66, s66, 0x80
	s_addc_u32 s67, s67, 0
	s_barrier
; #define LAS __attribute__((address_space(3)))
; #define BAR() { __builtin_amdgcn_sched_barrier(0); __builtin_amdgcn_s_barrier(); asm volatile("" ::: "memory"); __builtin_amdgcn_sched_barrier(0); }
; DI void gemm_stream2(const bf16_t* __restrict__ A, int lda, const bf16_t* __restrict__ Bt, int ldb, int K, int m0, int n0, ...
;     ...
;     for (int kt = 0; kt < nk; ++kt) {
;         const bool pf = (kt + 2 < nk) || has_next, more = (kt + 1 < nk) || has_next;
;         const bf16_t* pa = (kt + 2 < nk) ? ga + (kt + 2) * 64 : gan + (kt + 2 - nk) * 64;
;         const bf16_t* pb = (kt + 2 < nk) ? gb + (kt + 2) * 64 : gbn + (kt + 2 - nk) * 64;
;         const int plda = (kt + 2 < nk) ? lda : ldan, pldb = (kt + 2 < nk) ? ldb : ldbn;
;         const int s2 = st >= 1 ? st - 1 : 2;
;         const LAS char* base = lds + st * 49152;
; #pragma unroll
;         for (int ks = 0; ks < 2; ++ks) {
;             const unsigned fo = ks ? fo1 : fo0;
;             bf16x8 af[4], bfr[4];
; #pragma unroll
;             for (int i = 0; i < 4; ++i) { af[i] = *(const LAS bf16x8*)(base + aoff + i * 2048 + fo); bfr[i] = *(const LAS bf16x8*)(base + boff + i * 2048 + fo); }
;             if (ks == 1 && more) { if (pf) asm volatile("s_waitcnt vmcnt(3)" ::: "memory"); else asm volatile("s_waitcnt vmcnt(0)" ::: "memory"); }
;             if (pf) { PIECE(s2, ks * 3 + 0); PIECE(s2, ks * 3 + 1); PIECE(s2, ks * 3 + 2); }
;             asm volatile("s_waitcnt lgkmcnt(0)" ::: "memory");
;             BAR();
;             __builtin_amdgcn_s_setprio(1);
; #pragma unroll
;             for (int mi = 0; mi < 4; ++mi)
; #pragma unroll
;                 for (int ni = 0; ni < 4; ++ni) acc[mi][ni] = __builtin_amdgcn_mfma_f32_16x16x32_bf16(bfr[ni], af[mi], acc[mi][ni], 0, 0, 0);
;             __builtin_amdgcn_s_setprio(0);
;             BAR();
;         }
;         st = st == 2 ? 0 : st + 1;
;     }
;     if (grp == 0) BAR();
	s_waitcnt lgkmcnt(0)
	s_setprio 1
	v_mfma_f32_16x16x32_bf16 v[88:91], v[0:3], v[152:155], v[88:91]
	v_mfma_f32_16x16x32_bf16 v[92:95], v[8:11], v[152:155], v[92:95]
	v_mfma_f32_16x16x32_bf16 v[96:99], v[0:3], v[160:163], v[96:99]
	v_mfma_f32_16x16x32_bf16 v[100:103], v[8:11], v[160:163], v[100:103]
	v_mfma_f32_16x16x32_bf16 v[104:107], v[0:3], v[168:171], v[104:107]
	v_mfma_f32_16x16x32_bf16 v[108:111], v[8:11], v[168:171], v[108:111]
	v_mfma_f32_16x16x32_bf16 v[112:115], v[0:3], v[176:179], v[112:115]
	v_mfma_f32_16x16x32_bf16 v[116:119], v[8:11], v[176:179], v[116:119]
	v_mfma_f32_16x16x32_bf16 v[88:91], v[4:7], v[156:159], v[88:91]
	v_mfma_f32_16x16x32_bf16 v[92:95], v[12:15], v[156:159], v[92:95]
	v_mfma_f32_16x16x32_bf16 v[96:99], v[4:7], v[164:167], v[96:99]
	v_mfma_f32_16x16x32_bf16 v[100:103], v[12:15], v[164:167], v[100:103]
	v_mfma_f32_16x16x32_bf16 v[104:107], v[4:7], v[172:175], v[104:107]
	v_mfma_f32_16x16x32_bf16 v[108:111], v[12:15], v[172:175], v[108:111]
	v_mfma_f32_16x16x32_bf16 v[112:115], v[4:7], v[180:183], v[112:115]
	v_mfma_f32_16x16x32_bf16 v[116:119], v[12:15], v[180:183], v[116:119]
	s_setprio 0
	s_barrier
	s_add_i32 m0, s39, 0x1c000
	s_nop 0
	global_load_lds_dwordx4 v184, s[72:73]
	s_add_i32 m0, s39, 0x1c400
	s_nop 0
	global_load_lds_dwordx4 v185, s[72:73]
	s_add_u32 s72, s72, 0x80
	s_addc_u32 s73, s73, 0
	s_waitcnt vmcnt(6)
	s_barrier
	s_setprio 1
	v_mfma_f32_16x16x32_bf16 v[120:123], v[196:199], v[152:155], v[120:123]
	v_mfma_f32_16x16x32_bf16 v[124:127], v[204:207], v[152:155], v[124:127]
	v_mfma_f32_16x16x32_bf16 v[128:131], v[196:199], v[160:163], v[128:131]
	v_mfma_f32_16x16x32_bf16 v[132:135], v[204:207], v[160:163], v[132:135]
	v_mfma_f32_16x16x32_bf16 v[136:139], v[196:199], v[168:171], v[136:139]
	v_mfma_f32_16x16x32_bf16 v[140:143], v[204:207], v[168:171], v[140:143]
	v_mfma_f32_16x16x32_bf16 v[144:147], v[196:199], v[176:179], v[144:147]
	v_mfma_f32_16x16x32_bf16 v[148:151], v[204:207], v[176:179], v[148:151]
	v_mfma_f32_16x16x32_bf16 v[120:123], v[200:203], v[156:159], v[120:123]
	v_mfma_f32_16x16x32_bf16 v[124:127], v[208:211], v[156:159], v[124:127]
	v_mfma_f32_16x16x32_bf16 v[128:131], v[200:203], v[164:167], v[128:131]
	v_mfma_f32_16x16x32_bf16 v[132:135], v[208:211], v[164:167], v[132:135]
	v_mfma_f32_16x16x32_bf16 v[136:139], v[200:203], v[172:175], v[136:139]
	v_mfma_f32_16x16x32_bf16 v[140:143], v[208:211], v[172:175], v[140:143]
	v_mfma_f32_16x16x32_bf16 v[144:147], v[200:203], v[180:183], v[144:147]
	v_mfma_f32_16x16x32_bf16 v[148:151], v[208:211], v[180:183], v[148:151]
	s_setprio 0
	s_barrier
	s_sub_u32 s0, s0, 1
	s_cmp_lg_u32 s0, 0
	s_cbranch_scc1 .Lgu_kloop
	s_cmp_lg_u32 s54, 0
	s_cbranch_scc1 .Lgu_epi
	ds_read_b128 v[0:3], v188 offset:16
	ds_read_b128 v[4:7], v189 offset:16
	ds_read_b128 v[8:11], v188 offset:2064
	ds_read_b128 v[12:15], v189 offset:2064
	ds_read_b128 v[152:155], v186 offset:16
	ds_read_b128 v[156:159], v187 offset:16
	ds_read_b128 v[160:163], v186 offset:2064
	ds_read_b128 v[164:167], v187 offset:2064
	ds_read_b128 v[168:171], v186 offset:4112
	ds_read_b128 v[172:175], v187 offset:4112
	ds_read_b128 v[176:179], v186 offset:6160
	ds_read_b128 v[180:183], v187 offset:6160
	s_add_i32 m0, s39, 0xc000
	s_nop 0
	global_load_lds_dwordx4 v184, s[68:69]
	s_add_i32 m0, s39, 0xc400
	s_nop 0
	global_load_lds_dwordx4 v185, s[68:69]
	s_add_u32 s68, s68, 0x80
	s_addc_u32 s69, s69, 0
	s_barrier
	s_waitcnt lgkmcnt(0)
	s_setprio 1
	v_mfma_f32_16x16x32_bf16 v[24:27], v[0:3], v[152:155], v[24:27]
	v_mfma_f32_16x16x32_bf16 v[28:31], v[8:11], v[152:155], v[28:31]
	v_mfma_f32_16x16x32_bf16 v[32:35], v[0:3], v[160:163], v[32:35]
	v_mfma_f32_16x16x32_bf16 v[36:39], v[8:11], v[160:163], v[36:39]
	v_mfma_f32_16x16x32_bf16 v[40:43], v[0:3], v[168:171], v[40:43]
	v_mfma_f32_16x16x32_bf16 v[44:47], v[8:11], v[168:171], v[44:47]
	v_mfma_f32_16x16x32_bf16 v[48:51], v[0:3], v[176:179], v[48:51]
	v_mfma_f32_16x16x32_bf16 v[52:55], v[8:11], v[176:179], v[52:55]
	v_mfma_f32_16x16x32_bf16 v[24:27], v[4:7], v[156:159], v[24:27]
	v_mfma_f32_16x16x32_bf16 v[28:31], v[12:15], v[156:159], v[28:31]
	v_mfma_f32_16x16x32_bf16 v[32:35], v[4:7], v[164:167], v[32:35]
	v_mfma_f32_16x16x32_bf16 v[36:39], v[12:15], v[164:167], v[36:39]
	v_mfma_f32_16x16x32_bf16 v[40:43], v[4:7], v[172:175], v[40:43]
	v_mfma_f32_16x16x32_bf16 v[44:47], v[12:15], v[172:175], v[44:47]
	v_mfma_f32_16x16x32_bf16 v[48:51], v[4:7], v[180:183], v[48:51]
	v_mfma_f32_16x16x32_bf16 v[52:55], v[12:15], v[180:183], v[52:55]
	s_setprio 0
	s_barrier
	ds_read_b128 v[196:199], v188 offset:16400
	ds_read_b128 v[200:203], v189 offset:16400
	ds_read_b128 v[204:207], v188 offset:18448
	ds_read_b128 v[208:211], v189 offset:18448
	s_barrier
	s_waitcnt lgkmcnt(0)
	s_setprio 1
	v_mfma_f32_16x16x32_bf16 v[56:59], v[196:199], v[152:155], v[56:59]
	v_mfma_f32_16x16x32_bf16 v[60:63], v[204:207], v[152:155], v[60:63]
	v_mfma_f32_16x16x32_bf16 v[64:67], v[196:199], v[160:163], v[64:67]
	v_mfma_f32_16x16x32_bf16 v[68:71], v[204:207], v[160:163], v[68:71]
	v_mfma_f32_16x16x32_bf16 v[72:75], v[196:199], v[168:171], v[72:75]
	v_mfma_f32_16x16x32_bf16 v[76:79], v[204:207], v[168:171], v[76:79]
	v_mfma_f32_16x16x32_bf16 v[80:83], v[196:199], v[176:179], v[80:83]
	v_mfma_f32_16x16x32_bf16 v[84:87], v[204:207], v[176:179], v[84:87]
	v_mfma_f32_16x16x32_bf16 v[56:59], v[200:203], v[156:159], v[56:59]
	v_mfma_f32_16x16x32_bf16 v[60:63], v[208:211], v[156:159], v[60:63]
	v_mfma_f32_16x16x32_bf16 v[64:67], v[200:203], v[164:167], v[64:67]
	v_mfma_f32_16x16x32_bf16 v[68:71], v[208:211], v[164:167], v[68:71]
	v_mfma_f32_16x16x32_bf16 v[72:75], v[200:203], v[172:175], v[72:75]
	v_mfma_f32_16x16x32_bf16 v[76:79], v[208:211], v[172:175], v[76:79]
	v_mfma_f32_16x16x32_bf16 v[80:83], v[200:203], v[180:183], v[80:83]
	v_mfma_f32_16x16x32_bf16 v[84:87], v[208:211], v[180:183], v[84:87]
	s_setprio 0
	s_barrier
; #define LAS __attribute__((address_space(3)))
; #define BAR() { __builtin_amdgcn_sched_barrier(0); __builtin_amdgcn_s_barrier(); asm volatile("" ::: "memory"); __builtin_amdgcn_sched_barrier(0); }
; DI void gemm_stream2(const bf16_t* __restrict__ A, int lda, const bf16_t* __restrict__ Bt, int ldb, int K, int m0, int n0, ...
;     ...
;     for (int kt = 0; kt < nk; ++kt) {
;         const bool pf = (kt + 2 < nk) || has_next, more = (kt + 1 < nk) || has_next;
;         const bf16_t* pa = (kt + 2 < nk) ? ga + (kt + 2) * 64 : gan + (kt + 2 - nk) * 64;
;         const bf16_t* pb = (kt + 2 < nk) ? gb + (kt + 2) * 64 : gbn + (kt + 2 - nk) * 64;
;         const int plda = (kt + 2 < nk) ? lda : ldan, pldb = (kt + 2 < nk) ? ldb : ldbn;
;         const int s2 = st >= 1 ? st - 1 : 2;
;         const LAS char* base = lds + st * 49152;
; #pragma unroll
;         for (int ks = 0; ks < 2; ++ks) {
;             const unsigned fo = ks ? fo1 : fo0;
;             bf16x8 af[4], bfr[4];
; #pragma unroll
;             for (int i = 0; i < 4; ++i) { af[i] = *(const LAS bf16x8*)(base + aoff + i * 2048 + fo); bfr[i] = *(const LAS bf16x8*)(base + boff + i * 2048 + fo); }
;             if (ks == 1 && more) { if (pf) asm volatile("s_waitcnt vmcnt(3)" ::: "memory"); else asm volatile("s_waitcnt vmcnt(0)" ::: "memory"); }
;             if (pf) { PIECE(s2, ks * 3 + 0); PIECE(s2, ks * 3 + 1); PIECE(s2, ks * 3 + 2); }
;             asm volatile("s_waitcnt lgkmcnt(0)" ::: "memory");
;             BAR();
;             __builtin_amdgcn_s_setprio(1);
; #pragma unroll
;             for (int mi = 0; mi < 4; ++mi)
; #pragma unroll
;                 for (int ni = 0; ni < 4; ++ni) acc[mi][ni] = __builtin_amdgcn_mfma_f32_16x16x32_bf16(bfr[ni], af[mi], acc[mi][ni], 0, 0, 0);
;             __builtin_amdgcn_s_setprio(0);
;             BAR();
;         }
;         st = st == 2 ? 0 : st + 1;
;     }
;     if (grp == 0) BAR();
	ds_read_b128 v[152:155], v186 offset:16400
	ds_read_b128 v[156:159], v187 offset:16400
	ds_read_b128 v[160:163], v186 offset:18448
	ds_read_b128 v[164:167], v187 offset:18448
	ds_read_b128 v[168:171], v186 offset:20496
	ds_read_b128 v[172:175], v187 offset:20496
	ds_read_b128 v[176:179], v186 offset:22544
	ds_read_b128 v[180:183], v187 offset:22544
	s_waitcnt vmcnt(4)
	s_barrier
	s_waitcnt lgkmcnt(0)
	s_setprio 1
	v_mfma_f32_16x16x32_bf16 v[88:91], v[0:3], v[152:155], v[88:91]
	v_mfma_f32_16x16x32_bf16 v[92:95], v[8:11], v[152:155], v[92:95]
	v_mfma_f32_16x16x32_bf16 v[96:99], v[0:3], v[160:163], v[96:99]
	v_mfma_f32_16x16x32_bf16 v[100:103], v[8:11], v[160:163], v[100:103]
	v_mfma_f32_16x16x32_bf16 v[104:107], v[0:3], v[168:171], v[104:107]
	v_mfma_f32_16x16x32_bf16 v[108:111], v[8:11], v[168:171], v[108:111]
	v_mfma_f32_16x16x32_bf16 v[112:115], v[0:3], v[176:179], v[112:115]
	v_mfma_f32_16x16x32_bf16 v[116:119], v[8:11], v[176:179], v[116:119]
	v_mfma_f32_16x16x32_bf16 v[88:91], v[4:7], v[156:159], v[88:91]
	v_mfma_f32_16x16x32_bf16 v[92:95], v[12:15], v[156:159], v[92:95]
	v_mfma_f32_16x16x32_bf16 v[96:99], v[4:7], v[164:167], v[96:99]
	v_mfma_f32_16x16x32_bf16 v[100:103], v[12:15], v[164:167], v[100:103]
	v_mfma_f32_16x16x32_bf16 v[104:107], v[4:7], v[172:175], v[104:107]
	v_mfma_f32_16x16x32_bf16 v[108:111], v[12:15], v[172:175], v[108:111]
	v_mfma_f32_16x16x32_bf16 v[112:115], v[4:7], v[180:183], v[112:115]
	v_mfma_f32_16x16x32_bf16 v[116:119], v[12:15], v[180:183], v[116:119]
	s_setprio 0
	s_setprio 1
	v_mfma_f32_16x16x32_bf16 v[120:123], v[196:199], v[152:155], v[120:123]
	v_mfma_f32_16x16x32_bf16 v[124:127], v[204:207], v[152:155], v[124:127]
	v_mfma_f32_16x16x32_bf16 v[128:131], v[196:199], v[160:163], v[128:131]
	v_mfma_f32_16x16x32_bf16 v[132:135], v[204:207], v[160:163], v[132:135]
	v_mfma_f32_16x16x32_bf16 v[136:139], v[196:199], v[168:171], v[136:139]
	v_mfma_f32_16x16x32_bf16 v[140:143], v[204:207], v[168:171], v[140:143]
	v_mfma_f32_16x16x32_bf16 v[144:147], v[196:199], v[176:179], v[144:147]
	v_mfma_f32_16x16x32_bf16 v[148:151], v[204:207], v[176:179], v[148:151]
	v_mfma_f32_16x16x32_bf16 v[120:123], v[200:203], v[156:159], v[120:123]
	v_mfma_f32_16x16x32_bf16 v[124:127], v[208:211], v[156:159], v[124:127]
	v_mfma_f32_16x16x32_bf16 v[128:131], v[200:203], v[164:167], v[128:131]
	v_mfma_f32_16x16x32_bf16 v[132:135], v[208:211], v[164:167], v[132:135]
	v_mfma_f32_16x16x32_bf16 v[136:139], v[200:203], v[172:175], v[136:139]
	v_mfma_f32_16x16x32_bf16 v[140:143], v[208:211], v[172:175], v[140:143]
	v_mfma_f32_16x16x32_bf16 v[144:147], v[200:203], v[180:183], v[144:147]
	v_mfma_f32_16x16x32_bf16 v[148:151], v[208:211], v[180:183], v[148:151]
	s_setprio 0
	s_barrier
	ds_read_b128 v[0:3], v188 offset:32784
	ds_read_b128 v[4:7], v189 offset:32784
	ds_read_b128 v[8:11], v188 offset:34832
	ds_read_b128 v[12:15], v189 offset:34832
	ds_read_b128 v[152:155], v186 offset:32784
	ds_read_b128 v[156:159], v187 offset:32784
	ds_read_b128 v[160:163], v186 offset:34832
	ds_read_b128 v[164:167], v187 offset:34832
	ds_read_b128 v[168:171], v186 offset:36880
	ds_read_b128 v[172:175], v187 offset:36880
	ds_read_b128 v[176:179], v186 offset:38928
	ds_read_b128 v[180:183], v187 offset:38928
	s_waitcnt vmcnt(2)
	s_barrier
	s_waitcnt lgkmcnt(0)
	s_setprio 1
	v_mfma_f32_16x16x32_bf16 v[24:27], v[0:3], v[152:155], v[24:27]
	v_mfma_f32_16x16x32_bf16 v[28:31], v[8:11], v[152:155], v[28:31]
	v_mfma_f32_16x16x32_bf16 v[32:35], v[0:3], v[160:163], v[32:35]
	v_mfma_f32_16x16x32_bf16 v[36:39], v[8:11], v[160:163], v[36:39]
	v_mfma_f32_16x16x32_bf16 v[40:43], v[0:3], v[168:171], v[40:43]
	v_mfma_f32_16x16x32_bf16 v[44:47], v[8:11], v[168:171], v[44:47]
	v_mfma_f32_16x16x32_bf16 v[48:51], v[0:3], v[176:179], v[48:51]
	v_mfma_f32_16x16x32_bf16 v[52:55], v[8:11], v[176:179], v[52:55]
	v_mfma_f32_16x16x32_bf16 v[24:27], v[4:7], v[156:159], v[24:27]
	v_mfma_f32_16x16x32_bf16 v[28:31], v[12:15], v[156:159], v[28:31]
	v_mfma_f32_16x16x32_bf16 v[32:35], v[4:7], v[164:167], v[32:35]
	v_mfma_f32_16x16x32_bf16 v[36:39], v[12:15], v[164:167], v[36:39]
	v_mfma_f32_16x16x32_bf16 v[40:43], v[4:7], v[172:175], v[40:43]
	v_mfma_f32_16x16x32_bf16 v[44:47], v[12:15], v[172:175], v[44:47]
	v_mfma_f32_16x16x32_bf16 v[48:51], v[4:7], v[180:183], v[48:51]
	v_mfma_f32_16x16x32_bf16 v[52:55], v[12:15], v[180:183], v[52:55]
	s_setprio 0
	s_barrier
	ds_read_b128 v[196:199], v188 offset:49168
	ds_read_b128 v[200:203], v189 offset:49168
	ds_read_b128 v[204:207], v188 offset:51216
	ds_read_b128 v[208:211], v189 offset:51216
	s_waitcnt vmcnt(0)
	s_barrier
	s_waitcnt lgkmcnt(0)
	s_setprio 1
	v_mfma_f32_16x16x32_bf16 v[56:59], v[196:199], v[152:155], v[56:59]
	v_mfma_f32_16x16x32_bf16 v[60:63], v[204:207], v[152:155], v[60:63]
	v_mfma_f32_16x16x32_bf16 v[64:67], v[196:199], v[160:163], v[64:67]
	v_mfma_f32_16x16x32_bf16 v[68:71], v[204:207], v[160:163], v[68:71]
	v_mfma_f32_16x16x32_bf16 v[72:75], v[196:199], v[168:171], v[72:75]
	v_mfma_f32_16x16x32_bf16 v[76:79], v[204:207], v[168:171], v[76:79]
	v_mfma_f32_16x16x32_bf16 v[80:83], v[196:199], v[176:179], v[80:83]
	v_mfma_f32_16x16x32_bf16 v[84:87], v[204:207], v[176:179], v[84:87]
	v_mfma_f32_16x16x32_bf16 v[56:59], v[200:203], v[156:159], v[56:59]
	v_mfma_f32_16x16x32_bf16 v[60:63], v[208:211], v[156:159], v[60:63]
	v_mfma_f32_16x16x32_bf16 v[64:67], v[200:203], v[164:167], v[64:67]
	v_mfma_f32_16x16x32_bf16 v[68:71], v[208:211], v[164:167], v[68:71]
	v_mfma_f32_16x16x32_bf16 v[72:75], v[200:203], v[172:175], v[72:75]
	v_mfma_f32_16x16x32_bf16 v[76:79], v[208:211], v[172:175], v[76:79]
	v_mfma_f32_16x16x32_bf16 v[80:83], v[200:203], v[180:183], v[80:83]
	v_mfma_f32_16x16x32_bf16 v[84:87], v[208:211], v[180:183], v[84:87]
	s_setprio 0
	s_barrier
; DI unsigned pk2(float lo, float hi) { const f32x2 v = {lo, hi}; return __builtin_bit_cast(unsigned, __builtin_convertvector(v, bf2_t)); }
; #define BAR() { __builtin_amdgcn_sched_barrier(0); __builtin_amdgcn_s_barrier(); asm volatile("" ::: "memory"); __builtin_amdgcn_sched_barrier(0); }
; DI void gemm_stream2(const bf16_t* __restrict__ A, int lda, const bf16_t* __restrict__ Bt, int ldb, int K, int m0, int n0, ...
;     ...
;             BAR();
;         }
;         st = st == 2 ? 0 : st + 1;
;     }
;     if (grp == 0) BAR();
;     rg.st = st; rg.primed = has_next ? 1 : 0;
; DI void gemm_gu(const Params& p, size_t woff, int bid, int nb, char* smem, const int tid) {
;     ...
;         const int nb0 = n0 + wn * 64;
; #pragma unroll
;         for (int mi = 0; mi < 4; ++mi) {
;             const int row = m0 + wm * 64 + mi * 16 + r;
; #pragma unroll
;             for (int pr = 0; pr < 2; ++pr) {
;                 const f32x4 g = acc[mi][2 * pr], u = acc[mi][2 * pr + 1];
;                 float o[4];
; #pragma unroll
;                 for (int j = 0; j < 4; ++j) o[j] = g[j] * __builtin_amdgcn_rcpf(1.0f + __builtin_amdgcn_exp2f(-LOG2E * g[j])) * u[j];
;                 const int col = ((nb0 + pr * 32) >> 5) * 16 + q * 4;
;                 u32x2 w; w.x = pk2(o[0], o[1]); w.y = pk2(o[2], o[3]);
;                 *(u32x2*)(ACT + (size_t)row * DFF + col) = w;
	ds_read_b128 v[152:155], v186 offset:49168
	ds_read_b128 v[156:159], v187 offset:49168
	ds_read_b128 v[160:163], v186 offset:51216
	ds_read_b128 v[164:167], v187 offset:51216
	ds_read_b128 v[168:171], v186 offset:53264
	ds_read_b128 v[172:175], v187 offset:53264
	ds_read_b128 v[176:179], v186 offset:55312
	ds_read_b128 v[180:183], v187 offset:55312
	s_barrier
	s_waitcnt lgkmcnt(0)
	s_setprio 1
	v_mfma_f32_16x16x32_bf16 v[88:91], v[0:3], v[152:155], v[88:91]
	v_mfma_f32_16x16x32_bf16 v[92:95], v[8:11], v[152:155], v[92:95]
	v_mfma_f32_16x16x32_bf16 v[96:99], v[0:3], v[160:163], v[96:99]
	v_mfma_f32_16x16x32_bf16 v[100:103], v[8:11], v[160:163], v[100:103]
	v_mfma_f32_16x16x32_bf16 v[104:107], v[0:3], v[168:171], v[104:107]
	v_mfma_f32_16x16x32_bf16 v[108:111], v[8:11], v[168:171], v[108:111]
	v_mfma_f32_16x16x32_bf16 v[112:115], v[0:3], v[176:179], v[112:115]
	v_mfma_f32_16x16x32_bf16 v[116:119], v[8:11], v[176:179], v[116:119]
	v_mfma_f32_16x16x32_bf16 v[88:91], v[4:7], v[156:159], v[88:91]
	v_mfma_f32_16x16x32_bf16 v[92:95], v[12:15], v[156:159], v[92:95]
	v_mfma_f32_16x16x32_bf16 v[96:99], v[4:7], v[164:167], v[96:99]
	v_mfma_f32_16x16x32_bf16 v[100:103], v[12:15], v[164:167], v[100:103]
	v_mfma_f32_16x16x32_bf16 v[104:107], v[4:7], v[172:175], v[104:107]
	v_mfma_f32_16x16x32_bf16 v[108:111], v[12:15], v[172:175], v[108:111]
	v_mfma_f32_16x16x32_bf16 v[112:115], v[4:7], v[180:183], v[112:115]
	v_mfma_f32_16x16x32_bf16 v[116:119], v[12:15], v[180:183], v[116:119]
	s_setprio 0
	s_setprio 1
	v_mfma_f32_16x16x32_bf16 v[120:123], v[196:199], v[152:155], v[120:123]
	v_mfma_f32_16x16x32_bf16 v[124:127], v[204:207], v[152:155], v[124:127]
	v_mfma_f32_16x16x32_bf16 v[128:131], v[196:199], v[160:163], v[128:131]
	v_mfma_f32_16x16x32_bf16 v[132:135], v[204:207], v[160:163], v[132:135]
	v_mfma_f32_16x16x32_bf16 v[136:139], v[196:199], v[168:171], v[136:139]
	v_mfma_f32_16x16x32_bf16 v[140:143], v[204:207], v[168:171], v[140:143]
	v_mfma_f32_16x16x32_bf16 v[144:147], v[196:199], v[176:179], v[144:147]
	v_mfma_f32_16x16x32_bf16 v[148:151], v[204:207], v[176:179], v[148:151]
	v_mfma_f32_16x16x32_bf16 v[120:123], v[200:203], v[156:159], v[120:123]
	v_mfma_f32_16x16x32_bf16 v[124:127], v[208:211], v[156:159], v[124:127]
	v_mfma_f32_16x16x32_bf16 v[128:131], v[200:203], v[164:167], v[128:131]
	v_mfma_f32_16x16x32_bf16 v[132:135], v[208:211], v[164:167], v[132:135]
	v_mfma_f32_16x16x32_bf16 v[136:139], v[200:203], v[172:175], v[136:139]
	v_mfma_f32_16x16x32_bf16 v[140:143], v[208:211], v[172:175], v[140:143]
	v_mfma_f32_16x16x32_bf16 v[144:147], v[200:203], v[180:183], v[144:147]
	v_mfma_f32_16x16x32_bf16 v[148:151], v[208:211], v[180:183], v[148:151]
	s_setprio 0
	s_barrier
	s_cmp_lg_u32 s33, 0
	s_cbranch_scc1 .Lgu_epi
	s_barrier
.Lgu_epi:
	s_mul_i32 s1, s57, 0x160000
	s_lshl_b32 s62, s58, 8
	s_add_u32 s1, s1, s62
	s_add_u32 s1, s1, 0x52c0000
	s_add_u32 s2, s88, s1
	s_addc_u32 s3, s89, 0
	s_nop 7
	s_nop 7
	v_mul_f32_e32 v152, 0xbfb8aa3b, v24
	v_mul_f32_e32 v153, 0xbfb8aa3b, v25
	v_mul_f32_e32 v154, 0xbfb8aa3b, v26
	v_mul_f32_e32 v155, 0xbfb8aa3b, v27
	v_exp_f32_e32 v152, v152
	v_exp_f32_e32 v153, v153
	v_exp_f32_e32 v154, v154
	v_exp_f32_e32 v155, v155
	s_nop 0
	v_add_f32_e32 v152, 1.0, v152
	v_add_f32_e32 v153, 1.0, v153
	v_add_f32_e32 v154, 1.0, v154
	v_add_f32_e32 v155, 1.0, v155
	v_rcp_f32_e32 v152, v152
	v_rcp_f32_e32 v153, v153
	v_rcp_f32_e32 v154, v154
	v_rcp_f32_e32 v155, v155
	s_nop 0
	v_pk_mul_f32 v[152:153], v[24:25], v[152:153]
	v_pk_mul_f32 v[154:155], v[26:27], v[154:155]
	v_pk_mul_f32 v[152:153], v[28:29], v[152:153]
	v_pk_mul_f32 v[154:155], v[30:31], v[154:155]
	v_cvt_pk_bf16_f32 v152, v152, v153
	v_cvt_pk_bf16_f32 v153, v154, v155
	global_store_dwordx2 v237, v[152:153], s[2:3] offset:0
	v_mul_f32_e32 v156, 0xbfb8aa3b, v56
	v_mul_f32_e32 v157, 0xbfb8aa3b, v57
	v_mul_f32_e32 v158, 0xbfb8aa3b, v58
	v_mul_f32_e32 v159, 0xbfb8aa3b, v59
	v_exp_f32_e32 v156, v156
	v_exp_f32_e32 v157, v157
	v_exp_f32_e32 v158, v158
	v_exp_f32_e32 v159, v159
	s_nop 0
	v_add_f32_e32 v156, 1.0, v156
	v_add_f32_e32 v157, 1.0, v157
	v_add_f32_e32 v158, 1.0, v158
	v_add_f32_e32 v159, 1.0, v159
	v_rcp_f32_e32 v156, v156
	v_rcp_f32_e32 v157, v157
	v_rcp_f32_e32 v158, v158
	v_rcp_f32_e32 v159, v159
	s_nop 0
	v_pk_mul_f32 v[156:157], v[56:57], v[156:157]
	v_pk_mul_f32 v[158:159], v[58:59], v[158:159]
	v_pk_mul_f32 v[156:157], v[60:61], v[156:157]
	v_pk_mul_f32 v[158:159], v[62:63], v[158:159]
	v_cvt_pk_bf16_f32 v156, v156, v157
	v_cvt_pk_bf16_f32 v157, v158, v159
	global_store_dwordx2 v237, v[156:157], s[2:3] offset:128
	s_add_u32 s2, s2, 0x16000
	s_addc_u32 s3, s3, 0
	v_mul_f32_e32 v160, 0xbfb8aa3b, v32
	v_mul_f32_e32 v161, 0xbfb8aa3b, v33
	v_mul_f32_e32 v162, 0xbfb8aa3b, v34
	v_mul_f32_e32 v163, 0xbfb8aa3b, v35
	v_exp_f32_e32 v160, v160
	v_exp_f32_e32 v161, v161
	v_exp_f32_e32 v162, v162
	v_exp_f32_e32 v163, v163
	s_nop 0
	v_add_f32_e32 v160, 1.0, v160
	v_add_f32_e32 v161, 1.0, v161
	v_add_f32_e32 v162, 1.0, v162
	v_add_f32_e32 v163, 1.0, v163
	v_rcp_f32_e32 v160, v160
	v_rcp_f32_e32 v161, v161
	v_rcp_f32_e32 v162, v162
	v_rcp_f32_e32 v163, v163
	s_nop 0
	v_pk_mul_f32 v[160:161], v[32:33], v[160:161]
	v_pk_mul_f32 v[162:163], v[34:35], v[162:163]
	v_pk_mul_f32 v[160:161], v[36:37], v[160:161]
	v_pk_mul_f32 v[162:163], v[38:39], v[162:163]
	v_cvt_pk_bf16_f32 v160, v160, v161
	v_cvt_pk_bf16_f32 v161, v162, v163
	global_store_dwordx2 v237, v[160:161], s[2:3] offset:0
	v_mul_f32_e32 v164, 0xbfb8aa3b, v64
	v_mul_f32_e32 v165, 0xbfb8aa3b, v65
	v_mul_f32_e32 v166, 0xbfb8aa3b, v66
	v_mul_f32_e32 v167, 0xbfb8aa3b, v67
	v_exp_f32_e32 v164, v164
	v_exp_f32_e32 v165, v165
; DI unsigned pk2(float lo, float hi) { const f32x2 v = {lo, hi}; return __builtin_bit_cast(unsigned, __builtin_convertvector(v, bf2_t)); }
; DI void gemm_gu(const Params& p, size_t woff, int bid, int nb, char* smem, const int tid) {
;     ...
;         const int nb0 = n0 + wn * 64;
; #pragma unroll
;         for (int mi = 0; mi < 4; ++mi) {
;             const int row = m0 + wm * 64 + mi * 16 + r;
; #pragma unroll
;             for (int pr = 0; pr < 2; ++pr) {
;                 const f32x4 g = acc[mi][2 * pr], u = acc[mi][2 * pr + 1];
;                 float o[4];
; #pragma unroll
;                 for (int j = 0; j < 4; ++j) o[j] = g[j] * __builtin_amdgcn_rcpf(1.0f + __builtin_amdgcn_exp2f(-LOG2E * g[j])) * u[j];
;                 const int col = ((nb0 + pr * 32) >> 5) * 16 + q * 4;
;                 u32x2 w; w.x = pk2(o[0], o[1]); w.y = pk2(o[2], o[3]);
;                 *(u32x2*)(ACT + (size_t)row * DFF + col) = w;
;             }
;         }
	v_exp_f32_e32 v166, v166
	v_exp_f32_e32 v167, v167
	s_nop 0
	v_add_f32_e32 v164, 1.0, v164
	v_add_f32_e32 v165, 1.0, v165
	v_add_f32_e32 v166, 1.0, v166
	v_add_f32_e32 v167, 1.0, v167
	v_rcp_f32_e32 v164, v164
	v_rcp_f32_e32 v165, v165
	v_rcp_f32_e32 v166, v166
	v_rcp_f32_e32 v167, v167
	s_nop 0
	v_pk_mul_f32 v[164:165], v[64:65], v[164:165]
	v_pk_mul_f32 v[166:167], v[66:67], v[166:167]
	v_pk_mul_f32 v[164:165], v[68:69], v[164:165]
	v_pk_mul_f32 v[166:167], v[70:71], v[166:167]
	v_cvt_pk_bf16_f32 v164, v164, v165
	v_cvt_pk_bf16_f32 v165, v166, v167
	global_store_dwordx2 v237, v[164:165], s[2:3] offset:128
	s_add_u32 s2, s2, 0x16000
	s_addc_u32 s3, s3, 0
	v_mul_f32_e32 v168, 0xbfb8aa3b, v40
	v_mul_f32_e32 v169, 0xbfb8aa3b, v41
	v_mul_f32_e32 v170, 0xbfb8aa3b, v42
	v_mul_f32_e32 v171, 0xbfb8aa3b, v43
	v_exp_f32_e32 v168, v168
	v_exp_f32_e32 v169, v169
	v_exp_f32_e32 v170, v170
	v_exp_f32_e32 v171, v171
	s_nop 0
	v_add_f32_e32 v168, 1.0, v168
	v_add_f32_e32 v169, 1.0, v169
	v_add_f32_e32 v170, 1.0, v170
	v_add_f32_e32 v171, 1.0, v171
	v_rcp_f32_e32 v168, v168
	v_rcp_f32_e32 v169, v169
	v_rcp_f32_e32 v170, v170
	v_rcp_f32_e32 v171, v171
	s_nop 0
	v_pk_mul_f32 v[168:169], v[40:41], v[168:169]
	v_pk_mul_f32 v[170:171], v[42:43], v[170:171]
	v_pk_mul_f32 v[168:169], v[44:45], v[168:169]
	v_pk_mul_f32 v[170:171], v[46:47], v[170:171]
	v_cvt_pk_bf16_f32 v168, v168, v169
	v_cvt_pk_bf16_f32 v169, v170, v171
	global_store_dwordx2 v237, v[168:169], s[2:3] offset:0
	v_mul_f32_e32 v172, 0xbfb8aa3b, v72
	v_mul_f32_e32 v173, 0xbfb8aa3b, v73
	v_mul_f32_e32 v174, 0xbfb8aa3b, v74
	v_mul_f32_e32 v175, 0xbfb8aa3b, v75
	v_exp_f32_e32 v172, v172
	v_exp_f32_e32 v173, v173
	v_exp_f32_e32 v174, v174
	v_exp_f32_e32 v175, v175
	s_nop 0
	v_add_f32_e32 v172, 1.0, v172
	v_add_f32_e32 v173, 1.0, v173
	v_add_f32_e32 v174, 1.0, v174
	v_add_f32_e32 v175, 1.0, v175
	v_rcp_f32_e32 v172, v172
	v_rcp_f32_e32 v173, v173
	v_rcp_f32_e32 v174, v174
	v_rcp_f32_e32 v175, v175
	s_nop 0
	v_pk_mul_f32 v[172:173], v[72:73], v[172:173]
	v_pk_mul_f32 v[174:175], v[74:75], v[174:175]
	v_pk_mul_f32 v[172:173], v[76:77], v[172:173]
	v_pk_mul_f32 v[174:175], v[78:79], v[174:175]
	v_cvt_pk_bf16_f32 v172, v172, v173
	v_cvt_pk_bf16_f32 v173, v174, v175
	global_store_dwordx2 v237, v[172:173], s[2:3] offset:128
	s_add_u32 s2, s2, 0x16000
	s_addc_u32 s3, s3, 0
	v_mul_f32_e32 v152, 0xbfb8aa3b, v48
	v_mul_f32_e32 v153, 0xbfb8aa3b, v49
	v_mul_f32_e32 v154, 0xbfb8aa3b, v50
	v_mul_f32_e32 v155, 0xbfb8aa3b, v51
	v_exp_f32_e32 v152, v152
	v_exp_f32_e32 v153, v153
	v_exp_f32_e32 v154, v154
	v_exp_f32_e32 v155, v155
	s_nop 0
	v_add_f32_e32 v152, 1.0, v152
	v_add_f32_e32 v153, 1.0, v153
	v_add_f32_e32 v154, 1.0, v154
	v_add_f32_e32 v155, 1.0, v155
	v_rcp_f32_e32 v152, v152
	v_rcp_f32_e32 v153, v153
	v_rcp_f32_e32 v154, v154
	v_rcp_f32_e32 v155, v155
	s_nop 0
	v_pk_mul_f32 v[152:153], v[48:49], v[152:153]
	v_pk_mul_f32 v[154:155], v[50:51], v[154:155]
	v_pk_mul_f32 v[152:153], v[52:53], v[152:153]
	v_pk_mul_f32 v[154:155], v[54:55], v[154:155]
	v_cvt_pk_bf16_f32 v152, v152, v153
	v_cvt_pk_bf16_f32 v153, v154, v155
	global_store_dwordx2 v237, v[152:153], s[2:3] offset:0
	v_mul_f32_e32 v156, 0xbfb8aa3b, v80
	v_mul_f32_e32 v157, 0xbfb8aa3b, v81
	v_mul_f32_e32 v158, 0xbfb8aa3b, v82
	v_mul_f32_e32 v159, 0xbfb8aa3b, v83
	v_exp_f32_e32 v156, v156
	v_exp_f32_e32 v157, v157
	v_exp_f32_e32 v158, v158
	v_exp_f32_e32 v159, v159
	s_nop 0
	v_add_f32_e32 v156, 1.0, v156
	v_add_f32_e32 v157, 1.0, v157
	v_add_f32_e32 v158, 1.0, v158
	v_add_f32_e32 v159, 1.0, v159
	v_rcp_f32_e32 v156, v156
	v_rcp_f32_e32 v157, v157
	v_rcp_f32_e32 v158, v158
	v_rcp_f32_e32 v159, v159
	s_nop 0
	v_pk_mul_f32 v[156:157], v[80:81], v[156:157]
	v_pk_mul_f32 v[158:159], v[82:83], v[158:159]
	v_pk_mul_f32 v[156:157], v[84:85], v[156:157]
	v_pk_mul_f32 v[158:159], v[86:87], v[158:159]
	v_cvt_pk_bf16_f32 v156, v156, v157
	v_cvt_pk_bf16_f32 v157, v158, v159
	global_store_dwordx2 v237, v[156:157], s[2:3] offset:128
	s_add_u32 s2, s2, 0x6e000
	s_addc_u32 s3, s3, 0
	v_mul_f32_e32 v160, 0xbfb8aa3b, v88
	v_mul_f32_e32 v161, 0xbfb8aa3b, v89
	v_mul_f32_e32 v162, 0xbfb8aa3b, v90
	v_mul_f32_e32 v163, 0xbfb8aa3b, v91
	v_exp_f32_e32 v160, v160
	v_exp_f32_e32 v161, v161
	v_exp_f32_e32 v162, v162
	v_exp_f32_e32 v163, v163
	s_nop 0
	v_add_f32_e32 v160, 1.0, v160
	v_add_f32_e32 v161, 1.0, v161
	v_add_f32_e32 v162, 1.0, v162
	v_add_f32_e32 v163, 1.0, v163
	v_rcp_f32_e32 v160, v160
	v_rcp_f32_e32 v161, v161
	v_rcp_f32_e32 v162, v162
	v_rcp_f32_e32 v163, v163
	s_nop 0
	v_pk_mul_f32 v[160:161], v[88:89], v[160:161]
	v_pk_mul_f32 v[162:163], v[90:91], v[162:163]
	v_pk_mul_f32 v[160:161], v[92:93], v[160:161]
	v_pk_mul_f32 v[162:163], v[94:95], v[162:163]
	v_cvt_pk_bf16_f32 v160, v160, v161
	v_cvt_pk_bf16_f32 v161, v162, v163
	global_store_dwordx2 v237, v[160:161], s[2:3] offset:0
	v_mul_f32_e32 v164, 0xbfb8aa3b, v120
	v_mul_f32_e32 v165, 0xbfb8aa3b, v121
	v_mul_f32_e32 v166, 0xbfb8aa3b, v122
	v_mul_f32_e32 v167, 0xbfb8aa3b, v123
	v_exp_f32_e32 v164, v164
	v_exp_f32_e32 v165, v165
	v_exp_f32_e32 v166, v166
	v_exp_f32_e32 v167, v167
	s_nop 0
	v_add_f32_e32 v164, 1.0, v164
	v_add_f32_e32 v165, 1.0, v165
	v_add_f32_e32 v166, 1.0, v166
	v_add_f32_e32 v167, 1.0, v167
	v_rcp_f32_e32 v164, v164
	v_rcp_f32_e32 v165, v165
	v_rcp_f32_e32 v166, v166
	v_rcp_f32_e32 v167, v167
	s_nop 0
	v_pk_mul_f32 v[164:165], v[120:121], v[164:165]
	v_pk_mul_f32 v[166:167], v[122:123], v[166:167]
; DI unsigned pk2(float lo, float hi) { const f32x2 v = {lo, hi}; return __builtin_bit_cast(unsigned, __builtin_convertvector(v, bf2_t)); }
; DI void gemm_gu(const Params& p, size_t woff, int bid, int nb, char* smem, const int tid) {
;     ...
;         const int nb0 = n0 + wn * 64;
; #pragma unroll
;         for (int mi = 0; mi < 4; ++mi) {
;             const int row = m0 + wm * 64 + mi * 16 + r;
; #pragma unroll
;             for (int pr = 0; pr < 2; ++pr) {
;                 const f32x4 g = acc[mi][2 * pr], u = acc[mi][2 * pr + 1];
;                 float o[4];
; #pragma unroll
;                 for (int j = 0; j < 4; ++j) o[j] = g[j] * __builtin_amdgcn_rcpf(1.0f + __builtin_amdgcn_exp2f(-LOG2E * g[j])) * u[j];
;                 const int col = ((nb0 + pr * 32) >> 5) * 16 + q * 4;
;                 u32x2 w; w.x = pk2(o[0], o[1]); w.y = pk2(o[2], o[3]);
;                 *(u32x2*)(ACT + (size_t)row * DFF + col) = w;
;             }
;         }
;     }
	v_pk_mul_f32 v[164:165], v[124:125], v[164:165]
	v_pk_mul_f32 v[166:167], v[126:127], v[166:167]
	v_cvt_pk_bf16_f32 v164, v164, v165
	v_cvt_pk_bf16_f32 v165, v166, v167
	global_store_dwordx2 v237, v[164:165], s[2:3] offset:128
	s_add_u32 s2, s2, 0x16000
	s_addc_u32 s3, s3, 0
	v_mul_f32_e32 v168, 0xbfb8aa3b, v96
	v_mul_f32_e32 v169, 0xbfb8aa3b, v97
	v_mul_f32_e32 v170, 0xbfb8aa3b, v98
	v_mul_f32_e32 v171, 0xbfb8aa3b, v99
	v_exp_f32_e32 v168, v168
	v_exp_f32_e32 v169, v169
	v_exp_f32_e32 v170, v170
	v_exp_f32_e32 v171, v171
	s_nop 0
	v_add_f32_e32 v168, 1.0, v168
	v_add_f32_e32 v169, 1.0, v169
	v_add_f32_e32 v170, 1.0, v170
	v_add_f32_e32 v171, 1.0, v171
	v_rcp_f32_e32 v168, v168
	v_rcp_f32_e32 v169, v169
	v_rcp_f32_e32 v170, v170
	v_rcp_f32_e32 v171, v171
	s_nop 0
	v_pk_mul_f32 v[168:169], v[96:97], v[168:169]
	v_pk_mul_f32 v[170:171], v[98:99], v[170:171]
	v_pk_mul_f32 v[168:169], v[100:101], v[168:169]
	v_pk_mul_f32 v[170:171], v[102:103], v[170:171]
	v_cvt_pk_bf16_f32 v168, v168, v169
	v_cvt_pk_bf16_f32 v169, v170, v171
	global_store_dwordx2 v237, v[168:169], s[2:3] offset:0
	v_mul_f32_e32 v172, 0xbfb8aa3b, v128
	v_mul_f32_e32 v173, 0xbfb8aa3b, v129
	v_mul_f32_e32 v174, 0xbfb8aa3b, v130
	v_mul_f32_e32 v175, 0xbfb8aa3b, v131
	v_exp_f32_e32 v172, v172
	v_exp_f32_e32 v173, v173
	v_exp_f32_e32 v174, v174
	v_exp_f32_e32 v175, v175
	s_nop 0
	v_add_f32_e32 v172, 1.0, v172
	v_add_f32_e32 v173, 1.0, v173
	v_add_f32_e32 v174, 1.0, v174
	v_add_f32_e32 v175, 1.0, v175
	v_rcp_f32_e32 v172, v172
	v_rcp_f32_e32 v173, v173
	v_rcp_f32_e32 v174, v174
	v_rcp_f32_e32 v175, v175
	s_nop 0
	v_pk_mul_f32 v[172:173], v[128:129], v[172:173]
	v_pk_mul_f32 v[174:175], v[130:131], v[174:175]
	v_pk_mul_f32 v[172:173], v[132:133], v[172:173]
	v_pk_mul_f32 v[174:175], v[134:135], v[174:175]
	v_cvt_pk_bf16_f32 v172, v172, v173
	v_cvt_pk_bf16_f32 v173, v174, v175
	global_store_dwordx2 v237, v[172:173], s[2:3] offset:128
	s_add_u32 s2, s2, 0x16000
	s_addc_u32 s3, s3, 0
	v_mul_f32_e32 v152, 0xbfb8aa3b, v104
	v_mul_f32_e32 v153, 0xbfb8aa3b, v105
	v_mul_f32_e32 v154, 0xbfb8aa3b, v106
	v_mul_f32_e32 v155, 0xbfb8aa3b, v107
	v_exp_f32_e32 v152, v152
	v_exp_f32_e32 v153, v153
	v_exp_f32_e32 v154, v154
	v_exp_f32_e32 v155, v155
	s_nop 0
	v_add_f32_e32 v152, 1.0, v152
	v_add_f32_e32 v153, 1.0, v153
	v_add_f32_e32 v154, 1.0, v154
	v_add_f32_e32 v155, 1.0, v155
	v_rcp_f32_e32 v152, v152
	v_rcp_f32_e32 v153, v153
	v_rcp_f32_e32 v154, v154
	v_rcp_f32_e32 v155, v155
	s_nop 0
	v_pk_mul_f32 v[152:153], v[104:105], v[152:153]
	v_pk_mul_f32 v[154:155], v[106:107], v[154:155]
	v_pk_mul_f32 v[152:153], v[108:109], v[152:153]
	v_pk_mul_f32 v[154:155], v[110:111], v[154:155]
	v_cvt_pk_bf16_f32 v152, v152, v153
	v_cvt_pk_bf16_f32 v153, v154, v155
	global_store_dwordx2 v237, v[152:153], s[2:3] offset:0
	v_mul_f32_e32 v156, 0xbfb8aa3b, v136
	v_mul_f32_e32 v157, 0xbfb8aa3b, v137
	v_mul_f32_e32 v158, 0xbfb8aa3b, v138
	v_mul_f32_e32 v159, 0xbfb8aa3b, v139
	v_exp_f32_e32 v156, v156
	v_exp_f32_e32 v157, v157
	v_exp_f32_e32 v158, v158
	v_exp_f32_e32 v159, v159
	s_nop 0
	v_add_f32_e32 v156, 1.0, v156
	v_add_f32_e32 v157, 1.0, v157
	v_add_f32_e32 v158, 1.0, v158
	v_add_f32_e32 v159, 1.0, v159
	v_rcp_f32_e32 v156, v156
	v_rcp_f32_e32 v157, v157
	v_rcp_f32_e32 v158, v158
	v_rcp_f32_e32 v159, v159
	s_nop 0
	v_pk_mul_f32 v[156:157], v[136:137], v[156:157]
	v_pk_mul_f32 v[158:159], v[138:139], v[158:159]
	v_pk_mul_f32 v[156:157], v[140:141], v[156:157]
	v_pk_mul_f32 v[158:159], v[142:143], v[158:159]
	v_cvt_pk_bf16_f32 v156, v156, v157
	v_cvt_pk_bf16_f32 v157, v158, v159
	global_store_dwordx2 v237, v[156:157], s[2:3] offset:128
	s_add_u32 s2, s2, 0x16000
	s_addc_u32 s3, s3, 0
	v_mul_f32_e32 v160, 0xbfb8aa3b, v112
	v_mul_f32_e32 v161, 0xbfb8aa3b, v113
	v_mul_f32_e32 v162, 0xbfb8aa3b, v114
	v_mul_f32_e32 v163, 0xbfb8aa3b, v115
	v_exp_f32_e32 v160, v160
	v_exp_f32_e32 v161, v161
	v_exp_f32_e32 v162, v162
	v_exp_f32_e32 v163, v163
	s_nop 0
	v_add_f32_e32 v160, 1.0, v160
	v_add_f32_e32 v161, 1.0, v161
	v_add_f32_e32 v162, 1.0, v162
	v_add_f32_e32 v163, 1.0, v163
	v_rcp_f32_e32 v160, v160
	v_rcp_f32_e32 v161, v161
	v_rcp_f32_e32 v162, v162
	v_rcp_f32_e32 v163, v163
	s_nop 0
	v_pk_mul_f32 v[160:161], v[112:113], v[160:161]
	v_pk_mul_f32 v[162:163], v[114:115], v[162:163]
	v_pk_mul_f32 v[160:161], v[116:117], v[160:161]
	v_pk_mul_f32 v[162:163], v[118:119], v[162:163]
	v_cvt_pk_bf16_f32 v160, v160, v161
	v_cvt_pk_bf16_f32 v161, v162, v163
	global_store_dwordx2 v237, v[160:161], s[2:3] offset:0
	v_mul_f32_e32 v164, 0xbfb8aa3b, v144
	v_mul_f32_e32 v165, 0xbfb8aa3b, v145
	v_mul_f32_e32 v166, 0xbfb8aa3b, v146
	v_mul_f32_e32 v167, 0xbfb8aa3b, v147
	v_exp_f32_e32 v164, v164
	v_exp_f32_e32 v165, v165
	v_exp_f32_e32 v166, v166
	v_exp_f32_e32 v167, v167
	s_nop 0
	v_add_f32_e32 v164, 1.0, v164
	v_add_f32_e32 v165, 1.0, v165
	v_add_f32_e32 v166, 1.0, v166
	v_add_f32_e32 v167, 1.0, v167
	v_rcp_f32_e32 v164, v164
	v_rcp_f32_e32 v165, v165
	v_rcp_f32_e32 v166, v166
	v_rcp_f32_e32 v167, v167
	s_nop 0
	v_pk_mul_f32 v[164:165], v[144:145], v[164:165]
	v_pk_mul_f32 v[166:167], v[146:147], v[166:167]
	v_pk_mul_f32 v[164:165], v[148:149], v[164:165]
	v_pk_mul_f32 v[166:167], v[150:151], v[166:167]
	v_cvt_pk_bf16_f32 v164, v164, v165
	v_cvt_pk_bf16_f32 v165, v166, v167
	global_store_dwordx2 v237, v[164:165], s[2:3] offset:128
	s_cmp_eq_u32 s54, 0
	s_cbranch_scc1 .LBB0_860
	s_mov_b32 s51, s76
	s_mov_b32 s57, s59
	s_mov_b32 s58, s60
	s_branch .Lgu_tile
